# v8 + pool_stats rewrite + grid barrier release path shortened (last arriver bumps all XCD generation words)
# speedup vs baseline: 1.0031x; 1.0031x over previous
.LBB0_94:
	s_lshl_b32 s6, s48, 8
	s_add_u32 s6, s4, s6
	s_addc_u32 s7, s5, 0
	s_add_u32 s6, s6, 0x180000
	s_addc_u32 s7, s7, 0
	v_mov_b32_e32 v3, 1
	v_mov_b32_e32 v4, 0x1000
	global_atomic_add v3, v4, v3, s[6:7] offset:1024 sc0
	v_cvt_f32_u32_e32 v1, v2
	v_rcp_f32_e32 v1, v1
	v_mov_b32_e32 v5, 0
	s_waitcnt vmcnt(0)
	v_cvt_f32_u32_e32 v4, v3
	v_add_f32_e32 v4, 0.5, v4
	v_mul_f32_e32 v4, v4, v1
	v_cvt_u32_f32_e32 v4, v4
	v_mul_lo_u32 v1, v4, v2
	v_add_u32_e32 v1, v1, v2
	v_add_u32_e32 v3, 1, v3
	s_nop 0
	v_readfirstlane_b32 s8, v4
	v_readfirstlane_b32 s9, v1
	v_readfirstlane_b32 s10, v3
	s_add_u32 s14, s6, 0x2400
	s_addc_u32 s15, s7, 0
	s_cmp_lg_u32 s9, s10
	s_cbranch_scc1 .LXB_POLL_0
	buffer_wbl2 sc1
	s_waitcnt vmcnt(0) lgkmcnt(0)
	v_mov_b32_e32 v3, 1
	v_mov_b32_e32 v4, 0x183000
	global_atomic_add v3, v4, v3, s[4:5] offset:1024 sc0
	v_cvt_f32_u32_e32 v1, v0
	v_rcp_f32_e32 v1, v1
	s_waitcnt vmcnt(0)
	v_cvt_f32_u32_e32 v4, v3
	v_add_f32_e32 v4, 0.5, v4
	v_mul_f32_e32 v4, v4, v1
	v_cvt_u32_f32_e32 v4, v4
	v_mul_lo_u32 v1, v4, v0
	v_add_u32_e32 v1, v1, v0
	v_add_u32_e32 v3, 1, v3
	s_nop 0
	v_readfirstlane_b32 s9, v1
	v_readfirstlane_b32 s10, v3
	s_cmp_lg_u32 s9, s10
	s_cbranch_scc1 .LXB_POLL_0
	s_add_u32 s16, s4, 0x182400
	s_addc_u32 s17, s5, 0
	s_mov_b64 exec, 0x2ffff
	v_lshlrev_b32_e32 v4, 8, v248
	v_mov_b32_e32 v3, 1
	global_atomic_add v4, v3, s[16:17]
	s_mov_b64 exec, 1
	s_branch .LXB_ACQ_0
.LXB_POLL_0:
	s_mov_b32 s16, 0
.LXB_SPIN_0:
	global_load_dword v3, v5, s[14:15] sc1
	s_waitcnt vmcnt(0)
	v_readfirstlane_b32 s9, v3
	s_cmp_lg_u32 s9, s8
	s_cbranch_scc1 .LXB_ACQ_0
	s_sleep 1
	s_add_i32 s16, s16, 1
	s_cmp_lt_u32 s16, 0x200000
	s_cbranch_scc1 .LXB_SPIN_0
.LXB_ACQ_0:
	s_waitcnt vmcnt(0)
	buffer_inv sc1
	s_waitcnt vmcnt(0)


.LBB0_280:
	s_lshl_b32 s6, s49, 8
	s_add_u32 s6, s4, s6
	s_addc_u32 s7, s5, 0
	s_add_u32 s6, s6, 0x180000
	s_addc_u32 s7, s7, 0
	v_mov_b32_e32 v3, 1
	v_mov_b32_e32 v4, 0x1000
	global_atomic_add v3, v4, v3, s[6:7] offset:1024 sc0
	v_cvt_f32_u32_e32 v1, v2
	v_rcp_f32_e32 v1, v1
	v_mov_b32_e32 v5, 0
	s_waitcnt vmcnt(0)
	v_cvt_f32_u32_e32 v4, v3
	v_add_f32_e32 v4, 0.5, v4
	v_mul_f32_e32 v4, v4, v1
	v_cvt_u32_f32_e32 v4, v4
	v_mul_lo_u32 v1, v4, v2
	v_add_u32_e32 v1, v1, v2
	v_add_u32_e32 v3, 1, v3
	s_nop 0
	v_readfirstlane_b32 s8, v4
	v_readfirstlane_b32 s9, v1
	v_readfirstlane_b32 s10, v3
	s_add_u32 s14, s6, 0x2400
	s_addc_u32 s15, s7, 0
	s_cmp_lg_u32 s9, s10
	s_cbranch_scc1 .LXB_POLL_1
	buffer_wbl2 sc1
	s_waitcnt vmcnt(0) lgkmcnt(0)
	v_mov_b32_e32 v3, 1
	v_mov_b32_e32 v4, 0x183000
	global_atomic_add v3, v4, v3, s[4:5] offset:1024 sc0
	v_cvt_f32_u32_e32 v1, v0
	v_rcp_f32_e32 v1, v1
	s_waitcnt vmcnt(0)
	v_cvt_f32_u32_e32 v4, v3
	v_add_f32_e32 v4, 0.5, v4
	v_mul_f32_e32 v4, v4, v1
	v_cvt_u32_f32_e32 v4, v4
	v_mul_lo_u32 v1, v4, v0
	v_add_u32_e32 v1, v1, v0
	v_add_u32_e32 v3, 1, v3
	s_nop 0
	v_readfirstlane_b32 s9, v1
	v_readfirstlane_b32 s10, v3
	s_cmp_lg_u32 s9, s10
	s_cbranch_scc1 .LXB_POLL_1
	s_add_u32 s16, s4, 0x182400
	s_addc_u32 s17, s5, 0
	s_mov_b64 exec, 0x2ffff
	v_lshlrev_b32_e32 v4, 8, v248
	v_mov_b32_e32 v3, 1
	global_atomic_add v4, v3, s[16:17]
	s_mov_b64 exec, 1
	s_branch .LXB_ACQ_1

.LBB0_412:
	s_lshl_b32 s6, s50, 8
	s_add_u32 s6, s4, s6
	s_addc_u32 s7, s5, 0
	s_add_u32 s6, s6, 0x180000
	s_addc_u32 s7, s7, 0
	v_mov_b32_e32 v3, 1
	v_mov_b32_e32 v4, 0x1000
	global_atomic_add v3, v4, v3, s[6:7] offset:1024 sc0
	v_cvt_f32_u32_e32 v1, v2
	v_rcp_f32_e32 v1, v1
	v_mov_b32_e32 v5, 0
	s_waitcnt vmcnt(0)
	v_cvt_f32_u32_e32 v4, v3
	v_add_f32_e32 v4, 0.5, v4
	v_mul_f32_e32 v4, v4, v1
	v_cvt_u32_f32_e32 v4, v4
	v_mul_lo_u32 v1, v4, v2
	v_add_u32_e32 v1, v1, v2
	v_add_u32_e32 v3, 1, v3
	s_nop 0
	v_readfirstlane_b32 s8, v4
	v_readfirstlane_b32 s9, v1
	v_readfirstlane_b32 s10, v3
	s_add_u32 s14, s6, 0x2400
	s_addc_u32 s15, s7, 0
	s_cmp_lg_u32 s9, s10
	s_cbranch_scc1 .LXB_POLL_2
	buffer_wbl2 sc1
	s_waitcnt vmcnt(0) lgkmcnt(0)
	v_mov_b32_e32 v3, 1
	v_mov_b32_e32 v4, 0x183000
	global_atomic_add v3, v4, v3, s[4:5] offset:1024 sc0
	v_cvt_f32_u32_e32 v1, v0
	v_rcp_f32_e32 v1, v1
	s_waitcnt vmcnt(0)
	v_cvt_f32_u32_e32 v4, v3
	v_add_f32_e32 v4, 0.5, v4
	v_mul_f32_e32 v4, v4, v1
	v_cvt_u32_f32_e32 v4, v4
	v_mul_lo_u32 v1, v4, v0
	v_add_u32_e32 v1, v1, v0
	v_add_u32_e32 v3, 1, v3
	s_nop 0
	v_readfirstlane_b32 s9, v1
	v_readfirstlane_b32 s10, v3
	s_cmp_lg_u32 s9, s10
	s_cbranch_scc1 .LXB_POLL_2
	s_add_u32 s16, s4, 0x182400
	s_addc_u32 s17, s5, 0
	s_mov_b64 exec, 0x2ffff
	v_lshlrev_b32_e32 v4, 8, v248
	v_mov_b32_e32 v3, 1
	global_atomic_add v4, v3, s[16:17]
	s_mov_b64 exec, 1
	s_branch .LXB_ACQ_2
